# attention row-max trees: self-max canonicalisation pairs folded (16 fewer VALU ops per KV tile)
# speedup vs baseline: 1.0413x; 1.0007x over previous
; __device__ __forceinline__ void unit(unsigned char* ws, LAS unsigned char* lds, int b, int h, int mp, int qb, const int tid_in) {
;     ...
;             float mx = fmaxf(fmaxf(s[g][0][0], s[g][0][1]), fmaxf(s[g][0][2], s[g][0][3]));
; #pragma unroll
;             for (int jt = 1; jt < 4; ++jt) mx = fmaxf(mx, fmaxf(fmaxf(s[g][jt][0], s[g][jt][1]), fmaxf(s[g][jt][2], s[g][jt][3])));
;             if (__any(mx > 8.f)) {
;                 mx = fmaxf(mx, __shfl_xor(mx, 16)); mx = fmaxf(mx, __shfl_xor(mx, 32));
;                 const float dl = fmaxf(mx, 0.f), alpha = __builtin_amdgcn_exp2f(-dl);
;                 m[g] += dl; lacc[g] *= alpha;
; #pragma unroll
;                 for (int jt = 0; jt < 4; ++jt) s[g][jt] -= dl;
; #pragma unroll
;                 for (int et = 0; et < 8; ++et) o[g][et] *= alpha;
.LBB0_187:
	v_max_f32_e32 v180, v126, v127
	v_max_f32_e32 v181, v128, v129
	v_max_f32_e32 v182, v132, v133
	v_max3_f32 v182, v130, v131, v182
	v_max3_f32 v180, v180, v181, v182
	v_max_f32_e32 v181, v140, v141
	v_max_f32_e32 v182, v145, v145
	v_max_f32_e32 v183, v144, v144
	v_max_f32_e32 v182, v183, v182
	v_max3_f32 v181, v138, v139, v181
	v_max3_f32 v182, v142, v143, v182
	v_max3_f32 v180, v180, v181, v182
	v_cmp_lt_f32_e32 vcc, s94, v180
	s_cbranch_vccz .LBB0_189
	v_and_b32_e32 v182, 64, v187
	v_xor_b32_e32 v181, 16, v187
	v_add_u32_e32 v182, 64, v182
	v_cmp_lt_i32_e32 vcc, v181, v182
	s_nop 1
	v_cndmask_b32_e32 v181, v187, v181, vcc
	v_lshlrev_b32_e32 v181, 2, v181
	ds_bpermute_b32 v181, v181, v180
	v_max_f32_e32 v180, v180, v180
	s_waitcnt lgkmcnt(0)
	v_max_f32_e32 v181, v181, v181
	v_max_f32_e32 v180, v180, v181
	v_xor_b32_e32 v181, 32, v187
	v_cmp_lt_i32_e32 vcc, v181, v182
	s_nop 1
	v_cndmask_b32_e32 v181, v187, v181, vcc
	v_lshlrev_b32_e32 v181, 2, v181
	ds_bpermute_b32 v181, v181, v180
	s_waitcnt lgkmcnt(0)
	v_max3_f32 v181, v180, v181, 0
	v_exp_f32_e64 v180, -v181
	v_add_f32_e32 v175, v175, v181
	v_sub_f32_e32 v126, v126, v181
	v_sub_f32_e32 v127, v127, v181
	v_pk_mul_f32 v[72:73], v[72:73], v[180:181] op_sel_hi:[1,0]
	v_pk_mul_f32 v[70:71], v[70:71], v[180:181] op_sel_hi:[1,0]
	v_sub_f32_e32 v128, v128, v181
	v_sub_f32_e32 v129, v129, v181
	v_sub_f32_e32 v130, v130, v181
	v_sub_f32_e32 v131, v131, v181
	v_sub_f32_e32 v132, v132, v181
	v_sub_f32_e32 v133, v133, v181
	v_sub_f32_e32 v138, v138, v181
	v_sub_f32_e32 v139, v139, v181
	v_sub_f32_e32 v140, v140, v181
	v_sub_f32_e32 v141, v141, v181
	v_sub_f32_e32 v142, v142, v181
	v_sub_f32_e32 v143, v143, v181
	v_sub_f32_e32 v144, v144, v181
	v_sub_f32_e32 v145, v145, v181
	v_pk_mul_f32 v[68:69], v[68:69], v[180:181] op_sel_hi:[1,0]
	v_pk_mul_f32 v[66:67], v[66:67], v[180:181] op_sel_hi:[1,0]
	v_pk_mul_f32 v[64:65], v[64:65], v[180:181] op_sel_hi:[1,0]
	v_pk_mul_f32 v[62:63], v[62:63], v[180:181] op_sel_hi:[1,0]
	v_pk_mul_f32 v[60:61], v[60:61], v[180:181] op_sel_hi:[1,0]
	v_pk_mul_f32 v[58:59], v[58:59], v[180:181] op_sel_hi:[1,0]
	v_pk_mul_f32 v[56:57], v[56:57], v[180:181] op_sel_hi:[1,0]
	v_pk_mul_f32 v[54:55], v[54:55], v[180:181] op_sel_hi:[1,0]
	v_pk_mul_f32 v[52:53], v[52:53], v[180:181] op_sel_hi:[1,0]
	v_pk_mul_f32 v[50:51], v[50:51], v[180:181] op_sel_hi:[1,0]
	v_pk_mul_f32 v[48:49], v[48:49], v[180:181] op_sel_hi:[1,0]
	v_pk_mul_f32 v[46:47], v[46:47], v[180:181] op_sel_hi:[1,0]
	v_pk_mul_f32 v[44:45], v[44:45], v[180:181] op_sel_hi:[1,0]
	v_pk_mul_f32 v[42:43], v[42:43], v[180:181] op_sel_hi:[1,0]
	v_pk_mul_f32 v[36:37], v[36:37], v[180:181] op_sel_hi:[1,0]
	v_pk_mul_f32 v[34:35], v[34:35], v[180:181] op_sel_hi:[1,0]

; __device__ __forceinline__ void unit(unsigned char* ws, LAS unsigned char* lds, int b, int h, int mp, int qb, const int tid_in) {
;     ...
;             float mx = fmaxf(fmaxf(s[g][0][0], s[g][0][1]), fmaxf(s[g][0][2], s[g][0][3]));
; #pragma unroll
;             for (int jt = 1; jt < 4; ++jt) mx = fmaxf(mx, fmaxf(fmaxf(s[g][jt][0], s[g][jt][1]), fmaxf(s[g][jt][2], s[g][jt][3])));
;             if (__any(mx > 8.f)) {
;                 mx = fmaxf(mx, __shfl_xor(mx, 16)); mx = fmaxf(mx, __shfl_xor(mx, 32));
;                 const float dl = fmaxf(mx, 0.f), alpha = __builtin_amdgcn_exp2f(-dl);
;                 m[g] += dl; lacc[g] *= alpha;
; #pragma unroll
;                 for (int jt = 0; jt < 4; ++jt) s[g][jt] -= dl;
; #pragma unroll
;                 for (int et = 0; et < 8; ++et) o[g][et] *= alpha;
;             }
.LBB0_193:
	v_max_f32_e32 v180, v114, v115
	v_max_f32_e32 v181, v116, v117
	v_max_f32_e32 v182, v120, v121
	v_max3_f32 v182, v118, v119, v182
	v_max3_f32 v180, v180, v181, v182
	v_max_f32_e32 v181, v124, v125
	v_max_f32_e32 v182, v137, v137
	v_max_f32_e32 v183, v136, v136
	v_max_f32_e32 v182, v183, v182
	v_max3_f32 v181, v122, v123, v181
	v_max3_f32 v182, v134, v135, v182
	v_max3_f32 v180, v180, v181, v182
	v_cmp_lt_f32_e32 vcc, s94, v180
	s_cbranch_vccz .LBB0_195
	v_and_b32_e32 v182, 64, v187
	v_xor_b32_e32 v181, 16, v187
	v_add_u32_e32 v182, 64, v182
	v_cmp_lt_i32_e32 vcc, v181, v182
	s_nop 1
	v_cndmask_b32_e32 v181, v187, v181, vcc
	v_lshlrev_b32_e32 v181, 2, v181
	ds_bpermute_b32 v181, v181, v180
	v_max_f32_e32 v180, v180, v180
	s_waitcnt lgkmcnt(0)
	v_max_f32_e32 v181, v181, v181
	v_max_f32_e32 v180, v180, v181
	v_xor_b32_e32 v181, 32, v187
	v_cmp_lt_i32_e32 vcc, v181, v182
	s_nop 1
	v_cndmask_b32_e32 v181, v187, v181, vcc
	v_lshlrev_b32_e32 v181, 2, v181
	ds_bpermute_b32 v181, v181, v180
	s_waitcnt lgkmcnt(0)
	v_max3_f32 v181, v180, v181, 0
	v_exp_f32_e64 v180, -v181
	v_add_f32_e32 v177, v177, v181
	v_sub_f32_e32 v114, v114, v181
	v_sub_f32_e32 v115, v115, v181
	v_pk_mul_f32 v[40:41], v[40:41], v[180:181] op_sel_hi:[1,0]
	v_pk_mul_f32 v[38:39], v[38:39], v[180:181] op_sel_hi:[1,0]
	v_sub_f32_e32 v116, v116, v181
	v_sub_f32_e32 v117, v117, v181
	v_sub_f32_e32 v118, v118, v181
	v_sub_f32_e32 v119, v119, v181
	v_sub_f32_e32 v120, v120, v181
	v_sub_f32_e32 v121, v121, v181
	v_sub_f32_e32 v122, v122, v181
	v_sub_f32_e32 v123, v123, v181
	v_sub_f32_e32 v124, v124, v181
	v_sub_f32_e32 v125, v125, v181
	v_sub_f32_e32 v134, v134, v181
	v_sub_f32_e32 v135, v135, v181
	v_sub_f32_e32 v136, v136, v181
	v_sub_f32_e32 v137, v137, v181
	v_pk_mul_f32 v[32:33], v[32:33], v[180:181] op_sel_hi:[1,0]
	v_pk_mul_f32 v[30:31], v[30:31], v[180:181] op_sel_hi:[1,0]
	v_pk_mul_f32 v[28:29], v[28:29], v[180:181] op_sel_hi:[1,0]
	v_pk_mul_f32 v[26:27], v[26:27], v[180:181] op_sel_hi:[1,0]
	v_pk_mul_f32 v[24:25], v[24:25], v[180:181] op_sel_hi:[1,0]
	v_pk_mul_f32 v[22:23], v[22:23], v[180:181] op_sel_hi:[1,0]
	v_pk_mul_f32 v[12:13], v[12:13], v[180:181] op_sel_hi:[1,0]
	v_pk_mul_f32 v[10:11], v[10:11], v[180:181] op_sel_hi:[1,0]
	v_pk_mul_f32 v[20:21], v[20:21], v[180:181] op_sel_hi:[1,0]
	v_pk_mul_f32 v[18:19], v[18:19], v[180:181] op_sel_hi:[1,0]
	v_pk_mul_f32 v[16:17], v[16:17], v[180:181] op_sel_hi:[1,0]
	v_pk_mul_f32 v[14:15], v[14:15], v[180:181] op_sel_hi:[1,0]
	v_pk_mul_f32 v[8:9], v[8:9], v[180:181] op_sel_hi:[1,0]
	v_pk_mul_f32 v[6:7], v[6:7], v[180:181] op_sel_hi:[1,0]
	v_pk_mul_f32 v[4:5], v[4:5], v[180:181] op_sel_hi:[1,0]
	v_pk_mul_f32 v[2:3], v[2:3], v[180:181] op_sel_hi:[1,0]

; __device__ __forceinline__ void unit(unsigned char* ws, LAS unsigned char* lds, int b, int h, int mp, int qb, const int tid_in) {
;     ...
;             float mx = fmaxf(fmaxf(s[g][0][0], s[g][0][1]), fmaxf(s[g][0][2], s[g][0][3]));
; #pragma unroll
;             for (int jt = 1; jt < 4; ++jt) mx = fmaxf(mx, fmaxf(fmaxf(s[g][jt][0], s[g][jt][1]), fmaxf(s[g][jt][2], s[g][jt][3])));
;             if (__any(mx > 8.f)) {
;                 mx = fmaxf(mx, __shfl_xor(mx, 16)); mx = fmaxf(mx, __shfl_xor(mx, 32));
;                 const float dl = fmaxf(mx, 0.f), alpha = __builtin_amdgcn_exp2f(-dl);
;                 m[g] += dl; lacc[g] *= alpha;
; #pragma unroll
;                 for (int jt = 0; jt < 4; ++jt) s[g][jt] -= dl;
; #pragma unroll
;                 for (int et = 0; et < 8; ++et) o[g][et] *= alpha;
;             }
.LBB0_204:
	v_max_f32_e32 v83, v102, v103
	v_max_f32_e32 v84, v104, v105
	v_max_f32_e32 v85, v108, v109
	v_max3_f32 v85, v106, v107, v85
	v_max3_f32 v83, v83, v84, v85
	v_max_f32_e32 v84, v112, v113
	v_max_f32_e32 v85, v81, v81
	v_max_f32_e32 v86, v80, v80
	v_max_f32_e32 v85, v86, v85
	v_max3_f32 v84, v110, v111, v84
	v_max3_f32 v85, v78, v79, v85
	v_max3_f32 v83, v83, v84, v85
	v_cmp_lt_f32_e32 vcc, s94, v83
	s_cbranch_vccz .LBB0_206
	v_and_b32_e32 v85, 64, v187
	v_xor_b32_e32 v84, 16, v187
	v_add_u32_e32 v85, 64, v85
	v_cmp_lt_i32_e32 vcc, v84, v85
	s_nop 1
	v_cndmask_b32_e32 v84, v187, v84, vcc
	v_lshlrev_b32_e32 v84, 2, v84
	ds_bpermute_b32 v84, v84, v83
	v_max_f32_e32 v83, v83, v83
	s_waitcnt lgkmcnt(0)
	v_max_f32_e32 v84, v84, v84
	v_max_f32_e32 v83, v83, v84
	v_xor_b32_e32 v84, 32, v187
	v_cmp_lt_i32_e32 vcc, v84, v85
	s_nop 1
	v_cndmask_b32_e32 v84, v187, v84, vcc
	v_lshlrev_b32_e32 v84, 2, v84
	ds_bpermute_b32 v84, v84, v83
	s_waitcnt lgkmcnt(0)
	v_max3_f32 v83, v83, v84, 0
	v_exp_f32_e64 v84, -v83
	v_sub_f32_e32 v102, v102, v83
	v_sub_f32_e32 v103, v103, v83
	v_sub_f32_e32 v104, v104, v83
	v_pk_mul_f32 v[72:73], v[72:73], v[84:85] op_sel_hi:[1,0]
	v_pk_mul_f32 v[70:71], v[70:71], v[84:85] op_sel_hi:[1,0]
	v_sub_f32_e32 v105, v105, v83
	v_sub_f32_e32 v106, v106, v83
	v_sub_f32_e32 v107, v107, v83
	v_sub_f32_e32 v108, v108, v83
	v_sub_f32_e32 v109, v109, v83
	v_sub_f32_e32 v110, v110, v83
	v_sub_f32_e32 v111, v111, v83
	v_sub_f32_e32 v112, v112, v83
	v_sub_f32_e32 v113, v113, v83
	v_sub_f32_e32 v78, v78, v83
	v_sub_f32_e32 v79, v79, v83
	v_sub_f32_e32 v80, v80, v83
	v_sub_f32_e32 v81, v81, v83
	v_pk_mul_f32 v[68:69], v[68:69], v[84:85] op_sel_hi:[1,0]
	v_pk_mul_f32 v[66:67], v[66:67], v[84:85] op_sel_hi:[1,0]
	v_pk_mul_f32 v[64:65], v[64:65], v[84:85] op_sel_hi:[1,0]
	v_pk_mul_f32 v[62:63], v[62:63], v[84:85] op_sel_hi:[1,0]
	v_pk_mul_f32 v[60:61], v[60:61], v[84:85] op_sel_hi:[1,0]
	v_pk_mul_f32 v[58:59], v[58:59], v[84:85] op_sel_hi:[1,0]
	v_pk_mul_f32 v[56:57], v[56:57], v[84:85] op_sel_hi:[1,0]
	v_pk_mul_f32 v[54:55], v[54:55], v[84:85] op_sel_hi:[1,0]
	v_pk_mul_f32 v[52:53], v[52:53], v[84:85] op_sel_hi:[1,0]
	v_pk_mul_f32 v[50:51], v[50:51], v[84:85] op_sel_hi:[1,0]
	v_pk_mul_f32 v[48:49], v[48:49], v[84:85] op_sel_hi:[1,0]
	v_pk_mul_f32 v[46:47], v[46:47], v[84:85] op_sel_hi:[1,0]
	v_pk_mul_f32 v[44:45], v[44:45], v[84:85] op_sel_hi:[1,0]
	v_pk_mul_f32 v[42:43], v[42:43], v[84:85] op_sel_hi:[1,0]
	v_pk_mul_f32 v[36:37], v[36:37], v[84:85] op_sel_hi:[1,0]
	v_pk_mul_f32 v[34:35], v[34:35], v[84:85] op_sel_hi:[1,0]

; __device__ __forceinline__ void unit(unsigned char* ws, LAS unsigned char* lds, int b, int h, int mp, int qb, const int tid_in) {
;     ...
;             float mx = fmaxf(fmaxf(s[g][0][0], s[g][0][1]), fmaxf(s[g][0][2], s[g][0][3]));
; #pragma unroll
;             for (int jt = 1; jt < 4; ++jt) mx = fmaxf(mx, fmaxf(fmaxf(s[g][jt][0], s[g][jt][1]), fmaxf(s[g][jt][2], s[g][jt][3])));
;             if (__any(mx > 8.f)) {
;                 mx = fmaxf(mx, __shfl_xor(mx, 16)); mx = fmaxf(mx, __shfl_xor(mx, 32));
;                 const float dl = fmaxf(mx, 0.f), alpha = __builtin_amdgcn_exp2f(-dl);
;                 m[g] += dl; lacc[g] *= alpha;
; #pragma unroll
;                 for (int jt = 0; jt < 4; ++jt) s[g][jt] -= dl;
; #pragma unroll
;                 for (int et = 0; et < 8; ++et) o[g][et] *= alpha;
;             }
.LBB0_210:
	v_max_f32_e32 v82, v90, v91
	v_max_f32_e32 v83, v92, v93
	v_max_f32_e32 v84, v96, v97
	v_max3_f32 v84, v94, v95, v84
	v_max3_f32 v82, v82, v83, v84
	v_max_f32_e32 v83, v100, v101
	v_max_f32_e32 v84, v77, v77
	v_max_f32_e32 v85, v76, v76
	v_max_f32_e32 v84, v85, v84
	v_max3_f32 v83, v98, v99, v83
	v_max3_f32 v84, v74, v75, v84
	v_max3_f32 v82, v82, v83, v84
	v_cmp_lt_f32_e32 vcc, s94, v82
	s_cbranch_vccz .LBB0_170
	v_and_b32_e32 v84, 64, v187
	v_xor_b32_e32 v83, 16, v187
	v_add_u32_e32 v84, 64, v84
	v_cmp_lt_i32_e32 vcc, v83, v84
	s_nop 1
	v_cndmask_b32_e32 v83, v187, v83, vcc
	v_lshlrev_b32_e32 v83, 2, v83
	ds_bpermute_b32 v83, v83, v82
	v_max_f32_e32 v82, v82, v82
	s_waitcnt lgkmcnt(0)
	v_max_f32_e32 v83, v83, v83
	v_max_f32_e32 v82, v82, v83
	v_xor_b32_e32 v83, 32, v187
	v_cmp_lt_i32_e32 vcc, v83, v84
	s_nop 1
	v_cndmask_b32_e32 v83, v187, v83, vcc
	v_lshlrev_b32_e32 v83, 2, v83
	ds_bpermute_b32 v83, v83, v82
	s_waitcnt lgkmcnt(0)
	v_max3_f32 v83, v82, v83, 0
	v_exp_f32_e64 v82, -v83
	v_sub_f32_e32 v90, v90, v83
	v_sub_f32_e32 v91, v91, v83
	v_sub_f32_e32 v92, v92, v83
	v_pk_mul_f32 v[40:41], v[40:41], v[82:83] op_sel_hi:[1,0]
	v_pk_mul_f32 v[38:39], v[38:39], v[82:83] op_sel_hi:[1,0]
	v_sub_f32_e32 v93, v93, v83
	v_sub_f32_e32 v94, v94, v83
	v_sub_f32_e32 v95, v95, v83
	v_sub_f32_e32 v96, v96, v83
	v_sub_f32_e32 v97, v97, v83
	v_sub_f32_e32 v98, v98, v83
	v_sub_f32_e32 v99, v99, v83
	v_sub_f32_e32 v100, v100, v83
	v_sub_f32_e32 v101, v101, v83
	v_sub_f32_e32 v74, v74, v83
	v_sub_f32_e32 v75, v75, v83
	v_sub_f32_e32 v76, v76, v83
	v_sub_f32_e32 v77, v77, v83
	v_pk_mul_f32 v[32:33], v[32:33], v[82:83] op_sel_hi:[1,0]
	v_pk_mul_f32 v[30:31], v[30:31], v[82:83] op_sel_hi:[1,0]
	v_pk_mul_f32 v[28:29], v[28:29], v[82:83] op_sel_hi:[1,0]
	v_pk_mul_f32 v[26:27], v[26:27], v[82:83] op_sel_hi:[1,0]
	v_pk_mul_f32 v[24:25], v[24:25], v[82:83] op_sel_hi:[1,0]
	v_pk_mul_f32 v[22:23], v[22:23], v[82:83] op_sel_hi:[1,0]
	v_pk_mul_f32 v[12:13], v[12:13], v[82:83] op_sel_hi:[1,0]
	v_pk_mul_f32 v[10:11], v[10:11], v[82:83] op_sel_hi:[1,0]
	v_pk_mul_f32 v[20:21], v[20:21], v[82:83] op_sel_hi:[1,0]
	v_pk_mul_f32 v[18:19], v[18:19], v[82:83] op_sel_hi:[1,0]
	v_pk_mul_f32 v[16:17], v[16:17], v[82:83] op_sel_hi:[1,0]
	v_pk_mul_f32 v[14:15], v[14:15], v[82:83] op_sel_hi:[1,0]
	v_pk_mul_f32 v[8:9], v[8:9], v[82:83] op_sel_hi:[1,0]
	v_pk_mul_f32 v[6:7], v[6:7], v[82:83] op_sel_hi:[1,0]
	v_pk_mul_f32 v[4:5], v[4:5], v[82:83] op_sel_hi:[1,0]
	v_pk_mul_f32 v[2:3], v[2:3], v[82:83] op_sel_hi:[1,0]
	s_branch .LBB0_170
